# c1 + GEMM main loop heads aligned to 64B
# baseline (speedup 1.0000x reference)
; #define PG8_BAR __builtin_amdgcn_s_barrier()
; template <class Epi, class Sched>
; __device__ __forceinline__ void gemm_phase(LAS unsigned char* lds, const Gemm g, const Sched& S, const Epi& E, const int tid) {
;     ...
; #pragma unroll
;         for (int a = 0; a < 2; ++a)
; #pragma unroll
;             for (int b = 0; b < 2; ++b)
; #pragma unroll
;                 for (int m = 0; m < 4; ++m)
; #pragma unroll
;                     for (int n = 0; n < 2; ++n) acc[a][b][m][n] = (f32x4){0.f, 0.f, 0.f, 0.f};
;         cur = nxt; cA = nA; cB = nB; ++ui;
;         if (wr == 1) PG8_BAR;
.LBB0_181:
	s_add_u32 s16, s86, 0x100
	v_mov_b32_e32 v4, 0
	s_addc_u32 s17, s87, 0
	s_mov_b32 s12, -2
	v_mov_b32_e32 v5, v4
	v_mov_b32_e32 v6, v4
	v_mov_b32_e32 v7, v4
	v_mov_b32_e32 v36, v4
	v_mov_b32_e32 v37, v4
	v_mov_b32_e32 v38, v4
	v_mov_b32_e32 v39, v4
	v_mov_b32_e32 v8, v4
	v_mov_b32_e32 v9, v4
	v_mov_b32_e32 v10, v4
	v_mov_b32_e32 v11, v4
	v_mov_b32_e32 v40, v4
	v_mov_b32_e32 v41, v4
	v_mov_b32_e32 v42, v4
	v_mov_b32_e32 v43, v4
	v_mov_b32_e32 v12, v4
	v_mov_b32_e32 v13, v4
	v_mov_b32_e32 v14, v4
	v_mov_b32_e32 v15, v4
	v_mov_b32_e32 v44, v4
	v_mov_b32_e32 v45, v4
	v_mov_b32_e32 v46, v4
	v_mov_b32_e32 v47, v4
	v_mov_b32_e32 v16, v4
	v_mov_b32_e32 v17, v4
	v_mov_b32_e32 v18, v4
	v_mov_b32_e32 v19, v4
	v_mov_b32_e32 v48, v4
	v_mov_b32_e32 v49, v4
	v_mov_b32_e32 v50, v4
	v_mov_b32_e32 v51, v4
	v_mov_b32_e32 v68, v4
	v_mov_b32_e32 v69, v4
	v_mov_b32_e32 v70, v4
	v_mov_b32_e32 v71, v4
	v_mov_b32_e32 v100, v4
	v_mov_b32_e32 v101, v4
	v_mov_b32_e32 v102, v4
	v_mov_b32_e32 v103, v4
	v_mov_b32_e32 v72, v4
	v_mov_b32_e32 v73, v4
	v_mov_b32_e32 v74, v4
	v_mov_b32_e32 v75, v4
	v_mov_b32_e32 v104, v4
	v_mov_b32_e32 v105, v4
	v_mov_b32_e32 v106, v4
	v_mov_b32_e32 v107, v4
	v_mov_b32_e32 v76, v4
	v_mov_b32_e32 v77, v4
	v_mov_b32_e32 v78, v4
	v_mov_b32_e32 v79, v4
	v_mov_b32_e32 v108, v4
	v_mov_b32_e32 v109, v4
	v_mov_b32_e32 v110, v4
	v_mov_b32_e32 v111, v4
	v_mov_b32_e32 v80, v4
	v_mov_b32_e32 v81, v4
	v_mov_b32_e32 v82, v4
	v_mov_b32_e32 v83, v4
	v_mov_b32_e32 v112, v4
	v_mov_b32_e32 v113, v4
	v_mov_b32_e32 v114, v4
	v_mov_b32_e32 v115, v4
	v_mov_b32_e32 v20, v4
	v_mov_b32_e32 v21, v4
	v_mov_b32_e32 v22, v4
	v_mov_b32_e32 v23, v4
	v_mov_b32_e32 v52, v4
	v_mov_b32_e32 v53, v4
	v_mov_b32_e32 v54, v4
	v_mov_b32_e32 v55, v4
	v_mov_b32_e32 v24, v4
	v_mov_b32_e32 v25, v4
	v_mov_b32_e32 v26, v4
	v_mov_b32_e32 v27, v4
	v_mov_b32_e32 v56, v4
	v_mov_b32_e32 v57, v4
	v_mov_b32_e32 v58, v4
	v_mov_b32_e32 v59, v4
	v_mov_b32_e32 v28, v4
	v_mov_b32_e32 v29, v4
	v_mov_b32_e32 v30, v4
	v_mov_b32_e32 v31, v4
	v_mov_b32_e32 v60, v4
	v_mov_b32_e32 v61, v4
	v_mov_b32_e32 v62, v4
	v_mov_b32_e32 v63, v4
	v_mov_b32_e32 v32, v4
	v_mov_b32_e32 v33, v4
	v_mov_b32_e32 v34, v4
	v_mov_b32_e32 v35, v4
	v_mov_b32_e32 v64, v4
	v_mov_b32_e32 v65, v4
	v_mov_b32_e32 v66, v4
	v_mov_b32_e32 v67, v4
	v_mov_b32_e32 v84, v4
	v_mov_b32_e32 v85, v4
	v_mov_b32_e32 v86, v4
	v_mov_b32_e32 v87, v4
	v_mov_b32_e32 v116, v4
	v_mov_b32_e32 v117, v4
	v_mov_b32_e32 v118, v4
	v_mov_b32_e32 v119, v4
	v_mov_b32_e32 v88, v4
	v_mov_b32_e32 v89, v4
	v_mov_b32_e32 v90, v4
	v_mov_b32_e32 v91, v4
	v_mov_b32_e32 v120, v4
	v_mov_b32_e32 v121, v4
	v_mov_b32_e32 v122, v4
	v_mov_b32_e32 v123, v4
	v_mov_b32_e32 v92, v4
	v_mov_b32_e32 v93, v4
	v_mov_b32_e32 v94, v4
	v_mov_b32_e32 v95, v4
	v_mov_b32_e32 v124, v4
	v_mov_b32_e32 v125, v4
	v_mov_b32_e32 v126, v4
	v_mov_b32_e32 v127, v4
	v_mov_b32_e32 v96, v4
	v_mov_b32_e32 v97, v4
	v_mov_b32_e32 v98, v4
	v_mov_b32_e32 v99, v4
	v_mov_b32_e32 v128, v4
	v_mov_b32_e32 v129, v4
	v_mov_b32_e32 v130, v4
	v_mov_b32_e32 v131, v4
	.p2align	6

; template <class Epi, class Sched>
; __device__ __forceinline__ void gemm_phase(LAS unsigned char* lds, const Gemm g, const Sched& S, const Epi& E, const int tid) {
;     ...
;         const bool has_next = S.next(ui + 1, nxt);
;         const char* nA = has_next ? (const char*)g.A + (size_t)nxt.pm * tstepA : cA; const char* nB = has_next ? (const char*)g.Bt + (size_t)nxt.pn * tstepB : cB;
;     ...
; #pragma unroll
;         for (int a = 0; a < 2; ++a)
; #pragma unroll
;             for (int b = 0; b < 2; ++b)
; #pragma unroll
;                 for (int m = 0; m < 4; ++m)
; #pragma unroll
;                     for (int n = 0; n < 2; ++n) acc[a][b][m][n] = (f32x4){0.f, 0.f, 0.f, 0.f};
;         cur = nxt; cA = nA; cB = nB; ++ui;
.LBB0_207:
	s_ashr_i32 s43, s42, 31
	s_lshl_b64 s[12:13], s[42:43], 20
	v_readlane_b32 s16, v255, 26
	s_add_u32 s44, s16, s12
	s_addc_u32 s45, s75, s13
	s_and_b64 s[12:13], s[6:7], exec
	s_cselect_b32 s16, s45, s55
	s_cselect_b32 s17, s44, s54
	s_ashr_i32 s39, s38, 31
	s_lshl_b64 s[12:13], s[38:39], 20
	s_add_u32 s46, s1, s12
	s_addc_u32 s47, s56, s13
	s_and_b64 s[12:13], s[6:7], exec
	s_cselect_b32 s39, s47, s87
	s_cselect_b32 s43, s46, s86
	s_add_u32 s54, s54, 0x80080
	s_addc_u32 s55, s55, 0
	s_add_u32 s93, s86, 0x100
	v_mov_b32_e32 v4, 0
	s_addc_u32 s94, s87, 0
	s_mov_b32 s95, -2
	v_mov_b32_e32 v5, v4
	v_mov_b32_e32 v6, v4
	v_mov_b32_e32 v7, v4
	v_mov_b32_e32 v8, v4
	v_mov_b32_e32 v9, v4
	v_mov_b32_e32 v10, v4
	v_mov_b32_e32 v11, v4
	v_mov_b32_e32 v12, v4
	v_mov_b32_e32 v13, v4
	v_mov_b32_e32 v14, v4
	v_mov_b32_e32 v15, v4
	v_mov_b32_e32 v16, v4
	v_mov_b32_e32 v17, v4
	v_mov_b32_e32 v18, v4
	v_mov_b32_e32 v19, v4
	v_mov_b32_e32 v28, v4
	v_mov_b32_e32 v29, v4
	v_mov_b32_e32 v30, v4
	v_mov_b32_e32 v31, v4
	v_mov_b32_e32 v32, v4
	v_mov_b32_e32 v33, v4
	v_mov_b32_e32 v34, v4
	v_mov_b32_e32 v35, v4
	v_mov_b32_e32 v44, v4
	v_mov_b32_e32 v45, v4
	v_mov_b32_e32 v46, v4
	v_mov_b32_e32 v47, v4
	v_mov_b32_e32 v48, v4
	v_mov_b32_e32 v49, v4
	v_mov_b32_e32 v50, v4
	v_mov_b32_e32 v51, v4
	v_mov_b32_e32 v20, v4
	v_mov_b32_e32 v21, v4
	v_mov_b32_e32 v22, v4
	v_mov_b32_e32 v23, v4
	v_mov_b32_e32 v24, v4
	v_mov_b32_e32 v25, v4
	v_mov_b32_e32 v26, v4
	v_mov_b32_e32 v27, v4
	v_mov_b32_e32 v36, v4
	v_mov_b32_e32 v37, v4
	v_mov_b32_e32 v38, v4
	v_mov_b32_e32 v39, v4
	v_mov_b32_e32 v40, v4
	v_mov_b32_e32 v41, v4
	v_mov_b32_e32 v42, v4
	v_mov_b32_e32 v43, v4
	v_mov_b32_e32 v52, v4
	v_mov_b32_e32 v53, v4
	v_mov_b32_e32 v54, v4
	v_mov_b32_e32 v55, v4
	v_mov_b32_e32 v56, v4
	v_mov_b32_e32 v57, v4
	v_mov_b32_e32 v58, v4
	v_mov_b32_e32 v59, v4
	v_mov_b32_e32 v60, v4
	v_mov_b32_e32 v61, v4
	v_mov_b32_e32 v62, v4
	v_mov_b32_e32 v63, v4
	v_mov_b32_e32 v64, v4
	v_mov_b32_e32 v65, v4
	v_mov_b32_e32 v66, v4
	v_mov_b32_e32 v67, v4
	v_mov_b32_e32 v68, v4
	v_mov_b32_e32 v69, v4
	v_mov_b32_e32 v70, v4
	v_mov_b32_e32 v71, v4
	v_mov_b32_e32 v72, v4
	v_mov_b32_e32 v73, v4
	v_mov_b32_e32 v74, v4
	v_mov_b32_e32 v75, v4
	v_mov_b32_e32 v76, v4
	v_mov_b32_e32 v77, v4
	v_mov_b32_e32 v78, v4
	v_mov_b32_e32 v79, v4
	v_mov_b32_e32 v80, v4
	v_mov_b32_e32 v81, v4
	v_mov_b32_e32 v82, v4
	v_mov_b32_e32 v83, v4
	v_mov_b32_e32 v92, v4
	v_mov_b32_e32 v93, v4
	v_mov_b32_e32 v94, v4
	v_mov_b32_e32 v95, v4
	v_mov_b32_e32 v96, v4
	v_mov_b32_e32 v97, v4
	v_mov_b32_e32 v98, v4
	v_mov_b32_e32 v99, v4
	v_mov_b32_e32 v108, v4
	v_mov_b32_e32 v109, v4
	v_mov_b32_e32 v110, v4
	v_mov_b32_e32 v111, v4
	v_mov_b32_e32 v112, v4
	v_mov_b32_e32 v113, v4
	v_mov_b32_e32 v114, v4
	v_mov_b32_e32 v115, v4
	v_mov_b32_e32 v84, v4
	v_mov_b32_e32 v85, v4
	v_mov_b32_e32 v86, v4
	v_mov_b32_e32 v87, v4
	v_mov_b32_e32 v88, v4
	v_mov_b32_e32 v89, v4
	v_mov_b32_e32 v90, v4
	v_mov_b32_e32 v91, v4
	v_mov_b32_e32 v100, v4
	v_mov_b32_e32 v101, v4
	v_mov_b32_e32 v102, v4
	v_mov_b32_e32 v103, v4
	v_mov_b32_e32 v104, v4
	v_mov_b32_e32 v105, v4
	v_mov_b32_e32 v106, v4
	v_mov_b32_e32 v107, v4
	v_mov_b32_e32 v116, v4
	v_mov_b32_e32 v117, v4
	v_mov_b32_e32 v118, v4
	v_mov_b32_e32 v119, v4
	v_mov_b32_e32 v120, v4
	v_mov_b32_e32 v121, v4
	v_mov_b32_e32 v122, v4
	v_mov_b32_e32 v123, v4
	v_mov_b32_e32 v124, v4
	v_mov_b32_e32 v125, v4
	v_mov_b32_e32 v126, v4
	v_mov_b32_e32 v127, v4
	v_mov_b32_e32 v128, v4
	v_mov_b32_e32 v129, v4
	v_mov_b32_e32 v130, v4
	v_mov_b32_e32 v131, v4
	.p2align	6

; template <class Epi, class Sched>
; __device__ __forceinline__ void gemm_phase(LAS unsigned char* lds, const Gemm g, const Sched& S, const Epi& E, const int tid) {
;     ...
;         const bool has_next = S.next(ui + 1, nxt);
;         const char* nA = has_next ? (const char*)g.A + (size_t)nxt.pm * tstepA : cA; const char* nB = has_next ? (const char*)g.Bt + (size_t)nxt.pn * tstepB : cB;
;     ...
; #pragma unroll
;         for (int a = 0; a < 2; ++a)
; #pragma unroll
;             for (int b = 0; b < 2; ++b)
; #pragma unroll
;                 for (int m = 0; m < 4; ++m)
; #pragma unroll
;                     for (int n = 0; n < 2; ++n) acc[a][b][m][n] = (f32x4){0.f, 0.f, 0.f, 0.f};
;         cur = nxt; cA = nA; cB = nB; ++ui;
.LBB0_250:
	s_ashr_i32 s45, s44, 31
	s_lshl_b64 s[12:13], s[44:45], 20
	s_add_u32 s54, s56, s12
	s_addc_u32 s55, s57, s13
	s_and_b64 s[8:9], s[8:9], exec
	s_cselect_b32 s17, s55, s89
	s_cselect_b32 s45, s54, s88
	s_add_u32 vcc_lo, s88, 0x100
	v_mov_b32_e32 v4, 0
	s_addc_u32 vcc_hi, s89, 0
	s_mov_b32 s12, -2
	v_mov_b32_e32 v5, v4
	v_mov_b32_e32 v6, v4
	v_mov_b32_e32 v7, v4
	v_mov_b32_e32 v36, v4
	v_mov_b32_e32 v37, v4
	v_mov_b32_e32 v38, v4
	v_mov_b32_e32 v39, v4
	v_mov_b32_e32 v8, v4
	v_mov_b32_e32 v9, v4
	v_mov_b32_e32 v10, v4
	v_mov_b32_e32 v11, v4
	v_mov_b32_e32 v40, v4
	v_mov_b32_e32 v41, v4
	v_mov_b32_e32 v42, v4
	v_mov_b32_e32 v43, v4
	v_mov_b32_e32 v12, v4
	v_mov_b32_e32 v13, v4
	v_mov_b32_e32 v14, v4
	v_mov_b32_e32 v15, v4
	v_mov_b32_e32 v44, v4
	v_mov_b32_e32 v45, v4
	v_mov_b32_e32 v46, v4
	v_mov_b32_e32 v47, v4
	v_mov_b32_e32 v16, v4
	v_mov_b32_e32 v17, v4
	v_mov_b32_e32 v18, v4
	v_mov_b32_e32 v19, v4
	v_mov_b32_e32 v48, v4
	v_mov_b32_e32 v49, v4
	v_mov_b32_e32 v50, v4
	v_mov_b32_e32 v51, v4
	v_mov_b32_e32 v68, v4
	v_mov_b32_e32 v69, v4
	v_mov_b32_e32 v70, v4
	v_mov_b32_e32 v71, v4
	v_mov_b32_e32 v100, v4
	v_mov_b32_e32 v101, v4
	v_mov_b32_e32 v102, v4
	v_mov_b32_e32 v103, v4
	v_mov_b32_e32 v72, v4
	v_mov_b32_e32 v73, v4
	v_mov_b32_e32 v74, v4
	v_mov_b32_e32 v75, v4
	v_mov_b32_e32 v104, v4
	v_mov_b32_e32 v105, v4
	v_mov_b32_e32 v106, v4
	v_mov_b32_e32 v107, v4
	v_mov_b32_e32 v76, v4
	v_mov_b32_e32 v77, v4
	v_mov_b32_e32 v78, v4
	v_mov_b32_e32 v79, v4
	v_mov_b32_e32 v108, v4
	v_mov_b32_e32 v109, v4
	v_mov_b32_e32 v110, v4
	v_mov_b32_e32 v111, v4
	v_mov_b32_e32 v80, v4
	v_mov_b32_e32 v81, v4
	v_mov_b32_e32 v82, v4
	v_mov_b32_e32 v83, v4
	v_mov_b32_e32 v112, v4
	v_mov_b32_e32 v113, v4
	v_mov_b32_e32 v114, v4
	v_mov_b32_e32 v115, v4
	v_mov_b32_e32 v20, v4
	v_mov_b32_e32 v21, v4
	v_mov_b32_e32 v22, v4
	v_mov_b32_e32 v23, v4
	v_mov_b32_e32 v52, v4
	v_mov_b32_e32 v53, v4
	v_mov_b32_e32 v54, v4
	v_mov_b32_e32 v55, v4
	v_mov_b32_e32 v24, v4
	v_mov_b32_e32 v25, v4
	v_mov_b32_e32 v26, v4
	v_mov_b32_e32 v27, v4
	v_mov_b32_e32 v56, v4
	v_mov_b32_e32 v57, v4
	v_mov_b32_e32 v58, v4
	v_mov_b32_e32 v59, v4
	v_mov_b32_e32 v28, v4
	v_mov_b32_e32 v29, v4
	v_mov_b32_e32 v30, v4
	v_mov_b32_e32 v31, v4
	v_mov_b32_e32 v60, v4
	v_mov_b32_e32 v61, v4
	v_mov_b32_e32 v62, v4
	v_mov_b32_e32 v63, v4
	v_mov_b32_e32 v32, v4
	v_mov_b32_e32 v33, v4
	v_mov_b32_e32 v34, v4
	v_mov_b32_e32 v35, v4
	v_mov_b32_e32 v64, v4
	v_mov_b32_e32 v65, v4
	v_mov_b32_e32 v66, v4
	v_mov_b32_e32 v67, v4
	v_mov_b32_e32 v84, v4
	v_mov_b32_e32 v85, v4
	v_mov_b32_e32 v86, v4
	v_mov_b32_e32 v87, v4
	v_mov_b32_e32 v116, v4
	v_mov_b32_e32 v117, v4
	v_mov_b32_e32 v118, v4
	v_mov_b32_e32 v119, v4
	v_mov_b32_e32 v88, v4
	v_mov_b32_e32 v89, v4
	v_mov_b32_e32 v90, v4
	v_mov_b32_e32 v91, v4
	v_mov_b32_e32 v120, v4
	v_mov_b32_e32 v121, v4
	v_mov_b32_e32 v122, v4
	v_mov_b32_e32 v123, v4
	v_mov_b32_e32 v92, v4
	v_mov_b32_e32 v93, v4
	v_mov_b32_e32 v94, v4
	v_mov_b32_e32 v95, v4
	v_mov_b32_e32 v124, v4
	v_mov_b32_e32 v125, v4
	v_mov_b32_e32 v126, v4
	v_mov_b32_e32 v127, v4
	v_mov_b32_e32 v96, v4
	v_mov_b32_e32 v97, v4
	v_mov_b32_e32 v98, v4
	v_mov_b32_e32 v99, v4
	v_mov_b32_e32 v128, v4
	v_mov_b32_e32 v129, v4
	v_mov_b32_e32 v130, v4
	v_mov_b32_e32 v131, v4
	.p2align	6

; template <class Epi, class Sched>
; __device__ __forceinline__ void gemm_phase(LAS unsigned char* lds, const Gemm g, const Sched& S, const Epi& E, const int tid) {
;     ...
;         const bool has_next = S.next(ui + 1, nxt);
;         const char* nA = has_next ? (const char*)g.A + (size_t)nxt.pm * tstepA : cA; const char* nB = has_next ? (const char*)g.Bt + (size_t)nxt.pn * tstepB : cB;
;     ...
; #pragma unroll
;         for (int a = 0; a < 2; ++a)
; #pragma unroll
;             for (int b = 0; b < 2; ++b)
; #pragma unroll
;                 for (int m = 0; m < 4; ++m)
; #pragma unroll
;                     for (int n = 0; n < 2; ++n) acc[a][b][m][n] = (f32x4){0.f, 0.f, 0.f, 0.f};
;         cur = nxt; cA = nA; cB = nB; ++ui;
.LBB0_278:
	s_ashr_i32 s31, s30, 31
	s_lshl_b64 s[12:13], s[30:31], 20
	s_add_u32 s42, s56, s12
	s_addc_u32 s43, s57, s13
	s_and_b64 s[8:9], s[8:9], exec
	s_cselect_b32 s16, s43, s47
	s_cselect_b32 s17, s42, s46
	s_add_u32 s31, s46, 0x100
	v_mov_b32_e32 v4, 0
	s_addc_u32 s93, s47, 0
	s_mov_b32 s94, -2
	v_mov_b32_e32 v5, v4
	v_mov_b32_e32 v6, v4
	v_mov_b32_e32 v7, v4
	v_mov_b32_e32 v36, v4
	v_mov_b32_e32 v37, v4
	v_mov_b32_e32 v38, v4
	v_mov_b32_e32 v39, v4
	v_mov_b32_e32 v8, v4
	v_mov_b32_e32 v9, v4
	v_mov_b32_e32 v10, v4
	v_mov_b32_e32 v11, v4
	v_mov_b32_e32 v40, v4
	v_mov_b32_e32 v41, v4
	v_mov_b32_e32 v42, v4
	v_mov_b32_e32 v43, v4
	v_mov_b32_e32 v12, v4
	v_mov_b32_e32 v13, v4
	v_mov_b32_e32 v14, v4
	v_mov_b32_e32 v15, v4
	v_mov_b32_e32 v44, v4
	v_mov_b32_e32 v45, v4
	v_mov_b32_e32 v46, v4
	v_mov_b32_e32 v47, v4
	v_mov_b32_e32 v16, v4
	v_mov_b32_e32 v17, v4
	v_mov_b32_e32 v18, v4
	v_mov_b32_e32 v19, v4
	v_mov_b32_e32 v48, v4
	v_mov_b32_e32 v49, v4
	v_mov_b32_e32 v50, v4
	v_mov_b32_e32 v51, v4
	v_mov_b32_e32 v68, v4
	v_mov_b32_e32 v69, v4
	v_mov_b32_e32 v70, v4
	v_mov_b32_e32 v71, v4
	v_mov_b32_e32 v100, v4
	v_mov_b32_e32 v101, v4
	v_mov_b32_e32 v102, v4
	v_mov_b32_e32 v103, v4
	v_mov_b32_e32 v72, v4
	v_mov_b32_e32 v73, v4
	v_mov_b32_e32 v74, v4
	v_mov_b32_e32 v75, v4
	v_mov_b32_e32 v104, v4
	v_mov_b32_e32 v105, v4
	v_mov_b32_e32 v106, v4
	v_mov_b32_e32 v107, v4
	v_mov_b32_e32 v76, v4
	v_mov_b32_e32 v77, v4
	v_mov_b32_e32 v78, v4
	v_mov_b32_e32 v79, v4
	v_mov_b32_e32 v108, v4
	v_mov_b32_e32 v109, v4
	v_mov_b32_e32 v110, v4
	v_mov_b32_e32 v111, v4
	v_mov_b32_e32 v80, v4
	v_mov_b32_e32 v81, v4
	v_mov_b32_e32 v82, v4
	v_mov_b32_e32 v83, v4
	v_mov_b32_e32 v112, v4
	v_mov_b32_e32 v113, v4
	v_mov_b32_e32 v114, v4
	v_mov_b32_e32 v115, v4
	v_mov_b32_e32 v20, v4
	v_mov_b32_e32 v21, v4
	v_mov_b32_e32 v22, v4
	v_mov_b32_e32 v23, v4
	v_mov_b32_e32 v52, v4
	v_mov_b32_e32 v53, v4
	v_mov_b32_e32 v54, v4
	v_mov_b32_e32 v55, v4
	v_mov_b32_e32 v24, v4
	v_mov_b32_e32 v25, v4
	v_mov_b32_e32 v26, v4
	v_mov_b32_e32 v27, v4
	v_mov_b32_e32 v56, v4
	v_mov_b32_e32 v57, v4
	v_mov_b32_e32 v58, v4
	v_mov_b32_e32 v59, v4
	v_mov_b32_e32 v28, v4
	v_mov_b32_e32 v29, v4
	v_mov_b32_e32 v30, v4
	v_mov_b32_e32 v31, v4
	v_mov_b32_e32 v60, v4
	v_mov_b32_e32 v61, v4
	v_mov_b32_e32 v62, v4
	v_mov_b32_e32 v63, v4
	v_mov_b32_e32 v32, v4
	v_mov_b32_e32 v33, v4
	v_mov_b32_e32 v34, v4
	v_mov_b32_e32 v35, v4
	v_mov_b32_e32 v64, v4
	v_mov_b32_e32 v65, v4
	v_mov_b32_e32 v66, v4
	v_mov_b32_e32 v67, v4
	v_mov_b32_e32 v84, v4
	v_mov_b32_e32 v85, v4
	v_mov_b32_e32 v86, v4
	v_mov_b32_e32 v87, v4
	v_mov_b32_e32 v116, v4
	v_mov_b32_e32 v117, v4
	v_mov_b32_e32 v118, v4
	v_mov_b32_e32 v119, v4
	v_mov_b32_e32 v88, v4
	v_mov_b32_e32 v89, v4
	v_mov_b32_e32 v90, v4
	v_mov_b32_e32 v91, v4
	v_mov_b32_e32 v120, v4
	v_mov_b32_e32 v121, v4
	v_mov_b32_e32 v122, v4
	v_mov_b32_e32 v123, v4
	v_mov_b32_e32 v92, v4
	v_mov_b32_e32 v93, v4
	v_mov_b32_e32 v94, v4
	v_mov_b32_e32 v95, v4
	v_mov_b32_e32 v124, v4
	v_mov_b32_e32 v125, v4
	v_mov_b32_e32 v126, v4
	v_mov_b32_e32 v127, v4
	v_mov_b32_e32 v96, v4
	v_mov_b32_e32 v97, v4
	v_mov_b32_e32 v98, v4
	v_mov_b32_e32 v99, v4
	v_mov_b32_e32 v128, v4
	v_mov_b32_e32 v129, v4
	v_mov_b32_e32 v130, v4
	v_mov_b32_e32 v131, v4
	.p2align	6

; template <class Epi, class Sched>
; __device__ __forceinline__ void gemm_phase(LAS unsigned char* lds, const Gemm g, const Sched& S, const Epi& E, const int tid) {
;     ...
;         const bool has_next = S.next(ui + 1, nxt);
;         const char* nA = has_next ? (const char*)g.A + (size_t)nxt.pm * tstepA : cA; const char* nB = has_next ? (const char*)g.Bt + (size_t)nxt.pn * tstepB : cB;
;     ...
; #pragma unroll
;         for (int a = 0; a < 2; ++a)
; #pragma unroll
;             for (int b = 0; b < 2; ++b)
; #pragma unroll
;                 for (int m = 0; m < 4; ++m)
; #pragma unroll
;                     for (int n = 0; n < 2; ++n) acc[a][b][m][n] = (f32x4){0.f, 0.f, 0.f, 0.f};
;         cur = nxt; cA = nA; cB = nB; ++ui;
.LBB0_307:
	s_ashr_i32 s39, s38, 31
	s_lshl_b64 s[12:13], s[38:39], 19
	s_add_u32 s42, s26, s12
	s_addc_u32 s43, s56, s13
	s_and_b64 s[12:13], s[6:7], exec
	s_cselect_b32 s16, s43, s55
	s_cselect_b32 s17, s42, s54
	s_ashr_i32 s31, s30, 31
	s_lshl_b64 s[12:13], s[30:31], 19
	s_add_u32 s44, s57, s12
	s_addc_u32 s45, s58, s13
	s_and_b64 s[12:13], s[6:7], exec
	s_cselect_b32 s31, s45, s91
	s_cselect_b32 s39, s44, s90
	s_add_u32 s54, s54, 0x40080
	s_addc_u32 s55, s55, 0
	s_add_u32 s47, s90, 0x100
	v_mov_b32_e32 v4, 0
	s_addc_u32 s96, s91, 0
	s_mov_b32 s97, -2
	v_mov_b32_e32 v5, v4
	v_mov_b32_e32 v6, v4
	v_mov_b32_e32 v7, v4
	v_mov_b32_e32 v8, v4
	v_mov_b32_e32 v9, v4
	v_mov_b32_e32 v10, v4
	v_mov_b32_e32 v11, v4
	v_mov_b32_e32 v16, v4
	v_mov_b32_e32 v17, v4
	v_mov_b32_e32 v18, v4
	v_mov_b32_e32 v19, v4
	v_mov_b32_e32 v24, v4
	v_mov_b32_e32 v25, v4
	v_mov_b32_e32 v26, v4
	v_mov_b32_e32 v27, v4
	v_mov_b32_e32 v36, v4
	v_mov_b32_e32 v37, v4
	v_mov_b32_e32 v38, v4
	v_mov_b32_e32 v39, v4
	v_mov_b32_e32 v40, v4
	v_mov_b32_e32 v41, v4
	v_mov_b32_e32 v42, v4
	v_mov_b32_e32 v43, v4
	v_mov_b32_e32 v44, v4
	v_mov_b32_e32 v45, v4
	v_mov_b32_e32 v46, v4
	v_mov_b32_e32 v47, v4
	v_mov_b32_e32 v52, v4
	v_mov_b32_e32 v53, v4
	v_mov_b32_e32 v54, v4
	v_mov_b32_e32 v55, v4
	v_mov_b32_e32 v12, v4
	v_mov_b32_e32 v13, v4
	v_mov_b32_e32 v14, v4
	v_mov_b32_e32 v15, v4
	v_mov_b32_e32 v20, v4
	v_mov_b32_e32 v21, v4
	v_mov_b32_e32 v22, v4
	v_mov_b32_e32 v23, v4
	v_mov_b32_e32 v28, v4
	v_mov_b32_e32 v29, v4
	v_mov_b32_e32 v30, v4
	v_mov_b32_e32 v31, v4
	v_mov_b32_e32 v32, v4
	v_mov_b32_e32 v33, v4
	v_mov_b32_e32 v34, v4
	v_mov_b32_e32 v35, v4
	v_mov_b32_e32 v48, v4
	v_mov_b32_e32 v49, v4
	v_mov_b32_e32 v50, v4
	v_mov_b32_e32 v51, v4
	v_mov_b32_e32 v56, v4
	v_mov_b32_e32 v57, v4
	v_mov_b32_e32 v58, v4
	v_mov_b32_e32 v59, v4
	v_mov_b32_e32 v60, v4
	v_mov_b32_e32 v61, v4
	v_mov_b32_e32 v62, v4
	v_mov_b32_e32 v63, v4
	v_mov_b32_e32 v64, v4
	v_mov_b32_e32 v65, v4
	v_mov_b32_e32 v66, v4
	v_mov_b32_e32 v67, v4
	v_mov_b32_e32 v68, v4
	v_mov_b32_e32 v69, v4
	v_mov_b32_e32 v70, v4
	v_mov_b32_e32 v71, v4
	v_mov_b32_e32 v72, v4
	v_mov_b32_e32 v73, v4
	v_mov_b32_e32 v74, v4
	v_mov_b32_e32 v75, v4
	v_mov_b32_e32 v76, v4
	v_mov_b32_e32 v77, v4
	v_mov_b32_e32 v78, v4
	v_mov_b32_e32 v79, v4
	v_mov_b32_e32 v84, v4
	v_mov_b32_e32 v85, v4
	v_mov_b32_e32 v86, v4
	v_mov_b32_e32 v87, v4
	v_mov_b32_e32 v100, v4
	v_mov_b32_e32 v101, v4
	v_mov_b32_e32 v102, v4
	v_mov_b32_e32 v103, v4
	v_mov_b32_e32 v104, v4
	v_mov_b32_e32 v105, v4
	v_mov_b32_e32 v106, v4
	v_mov_b32_e32 v107, v4
	v_mov_b32_e32 v108, v4
	v_mov_b32_e32 v109, v4
	v_mov_b32_e32 v110, v4
	v_mov_b32_e32 v111, v4
	v_mov_b32_e32 v116, v4
	v_mov_b32_e32 v117, v4
	v_mov_b32_e32 v118, v4
	v_mov_b32_e32 v119, v4
	v_mov_b32_e32 v80, v4
	v_mov_b32_e32 v81, v4
	v_mov_b32_e32 v82, v4
	v_mov_b32_e32 v83, v4
	v_mov_b32_e32 v88, v4
	v_mov_b32_e32 v89, v4
	v_mov_b32_e32 v90, v4
	v_mov_b32_e32 v91, v4
	v_mov_b32_e32 v92, v4
	v_mov_b32_e32 v93, v4
	v_mov_b32_e32 v94, v4
	v_mov_b32_e32 v95, v4
	v_mov_b32_e32 v96, v4
	v_mov_b32_e32 v97, v4
	v_mov_b32_e32 v98, v4
	v_mov_b32_e32 v99, v4
	v_mov_b32_e32 v112, v4
	v_mov_b32_e32 v113, v4
	v_mov_b32_e32 v114, v4
	v_mov_b32_e32 v115, v4
	v_mov_b32_e32 v120, v4
	v_mov_b32_e32 v121, v4
	v_mov_b32_e32 v122, v4
	v_mov_b32_e32 v123, v4
	v_mov_b32_e32 v124, v4
	v_mov_b32_e32 v125, v4
	v_mov_b32_e32 v126, v4
	v_mov_b32_e32 v127, v4
	v_mov_b32_e32 v128, v4
	v_mov_b32_e32 v129, v4
	v_mov_b32_e32 v130, v4
	v_mov_b32_e32 v131, v4
	.p2align	6

; template <class Epi, class Sched>
; __device__ __forceinline__ void gemm_phase(LAS unsigned char* lds, const Gemm g, const Sched& S, const Epi& E, const int tid) {
;     ...
;         const bool has_next = S.next(ui + 1, nxt);
;         const char* nA = has_next ? (const char*)g.A + (size_t)nxt.pm * tstepA : cA; const char* nB = has_next ? (const char*)g.Bt + (size_t)nxt.pn * tstepB : cB;
;     ...
; #pragma unroll
;         for (int a = 0; a < 2; ++a)
; #pragma unroll
;             for (int b = 0; b < 2; ++b)
; #pragma unroll
;                 for (int m = 0; m < 4; ++m)
; #pragma unroll
;                     for (int n = 0; n < 2; ++n) acc[a][b][m][n] = (f32x4){0.f, 0.f, 0.f, 0.f};
;         cur = nxt; cA = nA; cB = nB; ++ui;
.LBB0_331:
	s_ashr_i32 s39, s38, 31
	s_lshl_b64 s[12:13], s[38:39], 19
	s_add_u32 s42, s26, s12
	s_addc_u32 s43, s56, s13
	s_and_b64 s[12:13], s[6:7], exec
	s_cselect_b32 s16, s43, s55
	s_cselect_b32 s17, s42, s54
	s_ashr_i32 s31, s30, 31
	s_lshl_b64 s[12:13], s[30:31], 19
	s_add_u32 s44, s57, s12
	s_addc_u32 s45, s58, s13
	s_and_b64 s[12:13], s[6:7], exec
	s_cselect_b32 s31, s45, s91
	s_cselect_b32 s39, s44, s90
	s_add_u32 s54, s54, 0x40080
	s_addc_u32 s55, s55, 0
	s_add_u32 s47, s90, 0x100
	v_mov_b32_e32 v4, 0
	s_addc_u32 s96, s91, 0
	s_mov_b32 s97, -2
	v_mov_b32_e32 v5, v4
	v_mov_b32_e32 v6, v4
	v_mov_b32_e32 v7, v4
	v_mov_b32_e32 v8, v4
	v_mov_b32_e32 v9, v4
	v_mov_b32_e32 v10, v4
	v_mov_b32_e32 v11, v4
	v_mov_b32_e32 v20, v4
	v_mov_b32_e32 v21, v4
	v_mov_b32_e32 v22, v4
	v_mov_b32_e32 v23, v4
	v_mov_b32_e32 v24, v4
	v_mov_b32_e32 v25, v4
	v_mov_b32_e32 v26, v4
	v_mov_b32_e32 v27, v4
	v_mov_b32_e32 v36, v4
	v_mov_b32_e32 v37, v4
	v_mov_b32_e32 v38, v4
	v_mov_b32_e32 v39, v4
	v_mov_b32_e32 v40, v4
	v_mov_b32_e32 v41, v4
	v_mov_b32_e32 v42, v4
	v_mov_b32_e32 v43, v4
	v_mov_b32_e32 v52, v4
	v_mov_b32_e32 v53, v4
	v_mov_b32_e32 v54, v4
	v_mov_b32_e32 v55, v4
	v_mov_b32_e32 v56, v4
	v_mov_b32_e32 v57, v4
	v_mov_b32_e32 v58, v4
	v_mov_b32_e32 v59, v4
	v_mov_b32_e32 v12, v4
	v_mov_b32_e32 v13, v4
	v_mov_b32_e32 v14, v4
	v_mov_b32_e32 v15, v4
	v_mov_b32_e32 v16, v4
	v_mov_b32_e32 v17, v4
	v_mov_b32_e32 v18, v4
	v_mov_b32_e32 v19, v4
	v_mov_b32_e32 v28, v4
	v_mov_b32_e32 v29, v4
	v_mov_b32_e32 v30, v4
	v_mov_b32_e32 v31, v4
	v_mov_b32_e32 v32, v4
	v_mov_b32_e32 v33, v4
	v_mov_b32_e32 v34, v4
	v_mov_b32_e32 v35, v4
	v_mov_b32_e32 v44, v4
	v_mov_b32_e32 v45, v4
	v_mov_b32_e32 v46, v4
	v_mov_b32_e32 v47, v4
	v_mov_b32_e32 v48, v4
	v_mov_b32_e32 v49, v4
	v_mov_b32_e32 v50, v4
	v_mov_b32_e32 v51, v4
	v_mov_b32_e32 v60, v4
	v_mov_b32_e32 v61, v4
	v_mov_b32_e32 v62, v4
	v_mov_b32_e32 v63, v4
	v_mov_b32_e32 v64, v4
	v_mov_b32_e32 v65, v4
	v_mov_b32_e32 v66, v4
	v_mov_b32_e32 v67, v4
	v_mov_b32_e32 v68, v4
	v_mov_b32_e32 v69, v4
	v_mov_b32_e32 v70, v4
	v_mov_b32_e32 v71, v4
	v_mov_b32_e32 v72, v4
	v_mov_b32_e32 v73, v4
	v_mov_b32_e32 v74, v4
	v_mov_b32_e32 v75, v4
	v_mov_b32_e32 v84, v4
	v_mov_b32_e32 v85, v4
	v_mov_b32_e32 v86, v4
	v_mov_b32_e32 v87, v4
	v_mov_b32_e32 v88, v4
	v_mov_b32_e32 v89, v4
	v_mov_b32_e32 v90, v4
	v_mov_b32_e32 v91, v4
	v_mov_b32_e32 v100, v4
	v_mov_b32_e32 v101, v4
	v_mov_b32_e32 v102, v4
	v_mov_b32_e32 v103, v4
	v_mov_b32_e32 v104, v4
	v_mov_b32_e32 v105, v4
	v_mov_b32_e32 v106, v4
	v_mov_b32_e32 v107, v4
	v_mov_b32_e32 v116, v4
	v_mov_b32_e32 v117, v4
	v_mov_b32_e32 v118, v4
	v_mov_b32_e32 v119, v4
	v_mov_b32_e32 v120, v4
	v_mov_b32_e32 v121, v4
	v_mov_b32_e32 v122, v4
	v_mov_b32_e32 v123, v4
	v_mov_b32_e32 v76, v4
	v_mov_b32_e32 v77, v4
	v_mov_b32_e32 v78, v4
	v_mov_b32_e32 v79, v4
	v_mov_b32_e32 v80, v4
	v_mov_b32_e32 v81, v4
	v_mov_b32_e32 v82, v4
	v_mov_b32_e32 v83, v4
	v_mov_b32_e32 v92, v4
	v_mov_b32_e32 v93, v4
	v_mov_b32_e32 v94, v4
	v_mov_b32_e32 v95, v4
	v_mov_b32_e32 v96, v4
	v_mov_b32_e32 v97, v4
	v_mov_b32_e32 v98, v4
	v_mov_b32_e32 v99, v4
	v_mov_b32_e32 v108, v4
	v_mov_b32_e32 v109, v4
	v_mov_b32_e32 v110, v4
	v_mov_b32_e32 v111, v4
	v_mov_b32_e32 v112, v4
	v_mov_b32_e32 v113, v4
	v_mov_b32_e32 v114, v4
	v_mov_b32_e32 v115, v4
	v_mov_b32_e32 v124, v4
	v_mov_b32_e32 v125, v4
	v_mov_b32_e32 v126, v4
	v_mov_b32_e32 v127, v4
	v_mov_b32_e32 v128, v4
	v_mov_b32_e32 v129, v4
	v_mov_b32_e32 v130, v4
	v_mov_b32_e32 v131, v4
	.p2align	6

; template <class Epi, class Sched>
; __device__ __forceinline__ void gemm_phase(LAS unsigned char* lds, const Gemm g, const Sched& S, const Epi& E, const int tid) {
;     ...
;         const bool has_next = S.next(ui + 1, nxt);
;         const char* nA = has_next ? (const char*)g.A + (size_t)nxt.pm * tstepA : cA; const char* nB = has_next ? (const char*)g.Bt + (size_t)nxt.pn * tstepB : cB;
;     ...
; #pragma unroll
;         for (int a = 0; a < 2; ++a)
; #pragma unroll
;             for (int b = 0; b < 2; ++b)
; #pragma unroll
;                 for (int m = 0; m < 4; ++m)
; #pragma unroll
;                     for (int n = 0; n < 2; ++n) acc[a][b][m][n] = (f32x4){0.f, 0.f, 0.f, 0.f};
;         cur = nxt; cA = nA; cB = nB; ++ui;
.LBB0_588:
	s_ashr_i32 s39, s38, 31
	s_lshl_b64 s[42:43], s[38:39], 20
	v_readlane_b32 s0, v255, 26
	s_add_u32 s42, s0, s42
	s_addc_u32 s43, s75, s43
	s_and_b64 s[44:45], s[6:7], exec
	s_cselect_b32 s0, s43, s47
	s_cselect_b32 s9, s42, s46
	s_ashr_i32 s31, s30, 31
	s_lshl_b64 s[44:45], s[30:31], 20
	s_add_u32 s44, s80, s44
	s_addc_u32 s45, s81, s45
	s_and_b64 s[84:85], s[6:7], exec
	s_cselect_b32 s11, s45, s55
	s_cselect_b32 s31, s44, s54
	s_add_u32 s46, s46, 0x80080
	s_addc_u32 s47, s47, 0
	s_add_u32 s39, s54, 0x100
	v_mov_b32_e32 v4, 0
	s_addc_u32 s86, s55, 0
	s_mov_b32 s87, -2
	v_mov_b32_e32 v5, v4
	v_mov_b32_e32 v6, v4
	v_mov_b32_e32 v7, v4
	v_mov_b32_e32 v8, v4
	v_mov_b32_e32 v9, v4
	v_mov_b32_e32 v10, v4
	v_mov_b32_e32 v11, v4
	v_mov_b32_e32 v12, v4
	v_mov_b32_e32 v13, v4
	v_mov_b32_e32 v14, v4
	v_mov_b32_e32 v15, v4
	v_mov_b32_e32 v16, v4
	v_mov_b32_e32 v17, v4
	v_mov_b32_e32 v18, v4
	v_mov_b32_e32 v19, v4
	v_mov_b32_e32 v20, v4
	v_mov_b32_e32 v21, v4
	v_mov_b32_e32 v22, v4
	v_mov_b32_e32 v23, v4
	v_mov_b32_e32 v24, v4
	v_mov_b32_e32 v25, v4
	v_mov_b32_e32 v26, v4
	v_mov_b32_e32 v27, v4
	v_mov_b32_e32 v28, v4
	v_mov_b32_e32 v29, v4
	v_mov_b32_e32 v30, v4
	v_mov_b32_e32 v31, v4
	v_mov_b32_e32 v32, v4
	v_mov_b32_e32 v33, v4
	v_mov_b32_e32 v34, v4
	v_mov_b32_e32 v35, v4
	v_mov_b32_e32 v68, v4
	v_mov_b32_e32 v69, v4
	v_mov_b32_e32 v70, v4
	v_mov_b32_e32 v71, v4
	v_mov_b32_e32 v72, v4
	v_mov_b32_e32 v73, v4
	v_mov_b32_e32 v74, v4
	v_mov_b32_e32 v75, v4
	v_mov_b32_e32 v76, v4
	v_mov_b32_e32 v77, v4
	v_mov_b32_e32 v78, v4
	v_mov_b32_e32 v79, v4
	v_mov_b32_e32 v80, v4
	v_mov_b32_e32 v81, v4
	v_mov_b32_e32 v82, v4
	v_mov_b32_e32 v83, v4
	v_mov_b32_e32 v84, v4
	v_mov_b32_e32 v85, v4
	v_mov_b32_e32 v86, v4
	v_mov_b32_e32 v87, v4
	v_mov_b32_e32 v88, v4
	v_mov_b32_e32 v89, v4
	v_mov_b32_e32 v90, v4
	v_mov_b32_e32 v91, v4
	v_mov_b32_e32 v92, v4
	v_mov_b32_e32 v93, v4
	v_mov_b32_e32 v94, v4
	v_mov_b32_e32 v95, v4
	v_mov_b32_e32 v96, v4
	v_mov_b32_e32 v97, v4
	v_mov_b32_e32 v98, v4
	v_mov_b32_e32 v99, v4
	v_mov_b32_e32 v36, v4
	v_mov_b32_e32 v37, v4
	v_mov_b32_e32 v38, v4
	v_mov_b32_e32 v39, v4
	v_mov_b32_e32 v40, v4
	v_mov_b32_e32 v41, v4
	v_mov_b32_e32 v42, v4
	v_mov_b32_e32 v43, v4
	v_mov_b32_e32 v44, v4
	v_mov_b32_e32 v45, v4
	v_mov_b32_e32 v46, v4
	v_mov_b32_e32 v47, v4
	v_mov_b32_e32 v48, v4
	v_mov_b32_e32 v49, v4
	v_mov_b32_e32 v50, v4
	v_mov_b32_e32 v51, v4
	v_mov_b32_e32 v52, v4
	v_mov_b32_e32 v53, v4
	v_mov_b32_e32 v54, v4
	v_mov_b32_e32 v55, v4
	v_mov_b32_e32 v56, v4
	v_mov_b32_e32 v57, v4
	v_mov_b32_e32 v58, v4
	v_mov_b32_e32 v59, v4
	v_mov_b32_e32 v60, v4
	v_mov_b32_e32 v61, v4
	v_mov_b32_e32 v62, v4
	v_mov_b32_e32 v63, v4
	v_mov_b32_e32 v64, v4
	v_mov_b32_e32 v65, v4
	v_mov_b32_e32 v66, v4
	v_mov_b32_e32 v67, v4
	v_mov_b32_e32 v108, v4
	v_mov_b32_e32 v109, v4
	v_mov_b32_e32 v110, v4
	v_mov_b32_e32 v111, v4
	v_mov_b32_e32 v112, v4
	v_mov_b32_e32 v113, v4
	v_mov_b32_e32 v114, v4
	v_mov_b32_e32 v115, v4
	v_mov_b32_e32 v116, v4
	v_mov_b32_e32 v117, v4
	v_mov_b32_e32 v118, v4
	v_mov_b32_e32 v119, v4
	v_mov_b32_e32 v120, v4
	v_mov_b32_e32 v121, v4
	v_mov_b32_e32 v122, v4
	v_mov_b32_e32 v123, v4
	v_mov_b32_e32 v124, v4
	v_mov_b32_e32 v125, v4
	v_mov_b32_e32 v126, v4
	v_mov_b32_e32 v127, v4
	v_mov_b32_e32 v128, v4
	v_mov_b32_e32 v129, v4
	v_mov_b32_e32 v130, v4
	v_mov_b32_e32 v131, v4
	v_mov_b32_e32 v132, v4
	v_mov_b32_e32 v133, v4
	v_mov_b32_e32 v134, v4
	v_mov_b32_e32 v135, v4
	v_mov_b32_e32 v136, v4
	v_mov_b32_e32 v137, v4
	v_mov_b32_e32 v138, v4
	v_mov_b32_e32 v139, v4
	.p2align	6
